# grid barrier: non-leader workgroups poll the global generation word directly instead of the per-XCD generation (one hop fewer), on top of P0+P7 edits
# speedup vs baseline: 1.0039x; 1.0030x over previous
; __device__ __forceinline__ unsigned xb_ld(unsigned* p)              { return __hip_atomic_load(p, __ATOMIC_RELAXED, __HIP_MEMORY_SCOPE_AGENT); }
; __device__ __forceinline__ unsigned xb_add(unsigned* p, unsigned v) { return __hip_atomic_fetch_add(p, v, __ATOMIC_RELAXED, __HIP_MEMORY_SCOPE_AGENT); }
; #define XB_SPIN(cond, bar) do { unsigned _sp = 0; while (cond) { __builtin_amdgcn_s_sleep(1); \
;     if ((++_sp & 255u) == 0u) { if (xb_ld(&(bar)[XB_TMO])) break; if (_sp > XB_SPIN_CAP) { atomicAdd(&(bar)[XB_TMO], 1u); break; } } } } while (0)
; __device__ __forceinline__ void xcd_barrier(const XcdBarrier& b) {
;     ...
;         const unsigned old = xb_add(&bar[XB_XSUB(b.x)], 1u);
;         const unsigned gen = old / nloc;
;         if (old + 1u == (gen + 1u) * nloc) {
;             __builtin_amdgcn_fence(__ATOMIC_RELEASE, "agent");
;             asm volatile("s_waitcnt vmcnt(0)" ::: "memory");
;             const unsigned og = xb_add(&bar[XB_TOP], 1u);
;             const unsigned tg = og / nx;
;             if (og + 1u == (tg + 1u) * nx) xb_add(&bar[XB_TOPGEN], 1u);
;             else XB_SPIN(xb_ld(&bar[XB_TOPGEN]) == tg, bar);
;             __builtin_amdgcn_fence(__ATOMIC_ACQUIRE, "agent");
;             xb_add(&bar[XB_XGEN(b.x)], 1u);
;             asm volatile("s_waitcnt vmcnt(0)" ::: "memory");
;         } else {
;             XB_SPIN(xb_ld(&bar[XB_XGEN(b.x)]) <= gen, bar);
;             __builtin_amdgcn_fence(__ATOMIC_ACQUIRE, "agent");
;             asm volatile("s_waitcnt vmcnt(0)" ::: "memory");
;         }
.LBB0_145:
	s_lshl_b32 s6, s33, 8
	s_add_u32 s6, s52, s6
	s_addc_u32 s7, s53, 0
	v_mov_b32_e32 v2, 0x1000
	v_mov_b32_e32 v4, 1
	global_atomic_add v4, v2, v4, s[6:7] offset:1024 sc0
	v_cvt_f32_u32_e32 v2, v3
	v_sub_u32_e32 v5, 0, v3
	v_rcp_iflag_f32_e32 v2, v2
	s_nop 0
	v_mul_f32_e32 v2, 0x4f7ffffe, v2
	v_cvt_u32_f32_e32 v2, v2
	v_mul_lo_u32 v5, v5, v2
	v_mul_hi_u32 v5, v2, v5
	v_add_u32_e32 v2, v2, v5
	s_waitcnt vmcnt(0)
	v_mul_hi_u32 v2, v4, v2
	v_mul_lo_u32 v5, v2, v3
	v_sub_u32_e32 v5, v4, v5
	v_add_u32_e32 v6, 1, v2
	v_cmp_ge_u32_e32 vcc, v5, v3
	v_add_u32_e32 v4, 1, v4
	s_nop 0
	v_cndmask_b32_e32 v2, v2, v6, vcc
	v_sub_u32_e32 v6, v5, v3
	v_cndmask_b32_e32 v5, v5, v6, vcc
	v_add_u32_e32 v6, 1, v2
	v_cmp_ge_u32_e32 vcc, v5, v3
	s_nop 1
	v_cndmask_b32_e32 v2, v2, v6, vcc
	v_mul_lo_u32 v5, v3, v2
	v_add_u32_e32 v3, v5, v3
	v_cmp_ne_u32_e32 vcc, v4, v3
	s_and_saveexec_b64 s[12:13], vcc
	s_xor_b64 s[12:13], exec, s[12:13]
	s_cbranch_execz .LBB0_159
	s_waitcnt lgkmcnt(0)
	v_mov_b32_e32 v1, 0x3100
	global_load_dword v1, v1, s[52:53] offset:1024 sc1
	s_add_u32 s18, s52, 0x3500
	s_addc_u32 s19, s53, 0
	s_waitcnt vmcnt(0)
	v_cmp_le_u32_e32 vcc, v1, v2
	s_and_saveexec_b64 s[14:15], vcc
	s_cbranch_execz .LBB0_158
	s_mov_b32 s35, 1
	s_mov_b64 s[22:23], 0
	v_mov_b32_e32 v1, 0
	s_branch .LBB0_149

; __device__ __forceinline__ unsigned xb_ld(unsigned* p)              { return __hip_atomic_load(p, __ATOMIC_RELAXED, __HIP_MEMORY_SCOPE_AGENT); }
; __device__ __forceinline__ unsigned xb_add(unsigned* p, unsigned v) { return __hip_atomic_fetch_add(p, v, __ATOMIC_RELAXED, __HIP_MEMORY_SCOPE_AGENT); }
; #define XB_SPIN(cond, bar) do { unsigned _sp = 0; while (cond) { __builtin_amdgcn_s_sleep(1); \
;     if ((++_sp & 255u) == 0u) { if (xb_ld(&(bar)[XB_TMO])) break; if (_sp > XB_SPIN_CAP) { atomicAdd(&(bar)[XB_TMO], 1u); break; } } } } while (0)
; __device__ __forceinline__ void xcd_barrier(const XcdBarrier& b) {
;     ...
;         const unsigned old = xb_add(&bar[XB_XSUB(b.x)], 1u);
;         const unsigned gen = old / nloc;
;         if (old + 1u == (gen + 1u) * nloc) {
;             __builtin_amdgcn_fence(__ATOMIC_RELEASE, "agent");
;             asm volatile("s_waitcnt vmcnt(0)" ::: "memory");
;             const unsigned og = xb_add(&bar[XB_TOP], 1u);
;             const unsigned tg = og / nx;
;             if (og + 1u == (tg + 1u) * nx) xb_add(&bar[XB_TOPGEN], 1u);
;             else XB_SPIN(xb_ld(&bar[XB_TOPGEN]) == tg, bar);
;             __builtin_amdgcn_fence(__ATOMIC_ACQUIRE, "agent");
;             xb_add(&bar[XB_XGEN(b.x)], 1u);
;             asm volatile("s_waitcnt vmcnt(0)" ::: "memory");
;         } else {
;             XB_SPIN(xb_ld(&bar[XB_XGEN(b.x)]) <= gen, bar);
;             __builtin_amdgcn_fence(__ATOMIC_ACQUIRE, "agent");
;             asm volatile("s_waitcnt vmcnt(0)" ::: "memory");
;         }
.LBB0_234:
	s_lshl_b32 s12, s33, 8
	s_add_u32 s12, s52, s12
	s_addc_u32 s13, s53, 0
	v_mov_b32_e32 v2, 0x1000
	v_mov_b32_e32 v4, 1
	global_atomic_add v4, v2, v4, s[12:13] offset:1024 sc0
	v_cvt_f32_u32_e32 v2, v3
	v_sub_u32_e32 v5, 0, v3
	v_rcp_iflag_f32_e32 v2, v2
	s_nop 0
	v_mul_f32_e32 v2, 0x4f7ffffe, v2
	v_cvt_u32_f32_e32 v2, v2
	v_mul_lo_u32 v5, v5, v2
	v_mul_hi_u32 v5, v2, v5
	v_add_u32_e32 v2, v2, v5
	s_waitcnt vmcnt(0)
	v_mul_hi_u32 v2, v4, v2
	v_mul_lo_u32 v5, v2, v3
	v_sub_u32_e32 v5, v4, v5
	v_add_u32_e32 v6, 1, v2
	v_cmp_ge_u32_e32 vcc, v5, v3
	v_add_u32_e32 v4, 1, v4
	s_nop 0
	v_cndmask_b32_e32 v2, v2, v6, vcc
	v_sub_u32_e32 v6, v5, v3
	v_cndmask_b32_e32 v5, v5, v6, vcc
	v_add_u32_e32 v6, 1, v2
	v_cmp_ge_u32_e32 vcc, v5, v3
	s_nop 1
	v_cndmask_b32_e32 v2, v2, v6, vcc
	v_mul_lo_u32 v5, v3, v2
	v_add_u32_e32 v3, v5, v3
	v_cmp_ne_u32_e32 vcc, v4, v3
	s_and_saveexec_b64 s[14:15], vcc
	s_xor_b64 s[14:15], exec, s[14:15]
	s_cbranch_execz .LBB0_248
	s_waitcnt lgkmcnt(0)
	v_mov_b32_e32 v1, 0x3100
	global_load_dword v1, v1, s[52:53] offset:1024 sc1
	s_add_u32 s22, s52, 0x3500
	s_addc_u32 s23, s53, 0
	s_waitcnt vmcnt(0)
	v_cmp_le_u32_e32 vcc, v1, v2
	s_and_saveexec_b64 s[18:19], vcc
	s_cbranch_execz .LBB0_247
	s_mov_b32 s35, 1
	s_mov_b64 s[24:25], 0
	v_mov_b32_e32 v1, 0
	s_branch .LBB0_238

; __device__ __forceinline__ unsigned xb_ld(unsigned* p)              { return __hip_atomic_load(p, __ATOMIC_RELAXED, __HIP_MEMORY_SCOPE_AGENT); }
; __device__ __forceinline__ unsigned xb_add(unsigned* p, unsigned v) { return __hip_atomic_fetch_add(p, v, __ATOMIC_RELAXED, __HIP_MEMORY_SCOPE_AGENT); }
; #define XB_SPIN(cond, bar) do { unsigned _sp = 0; while (cond) { __builtin_amdgcn_s_sleep(1); \
;     if ((++_sp & 255u) == 0u) { if (xb_ld(&(bar)[XB_TMO])) break; if (_sp > XB_SPIN_CAP) { atomicAdd(&(bar)[XB_TMO], 1u); break; } } } } while (0)
; __device__ __forceinline__ void xcd_barrier(const XcdBarrier& b) {
;     ...
;         const unsigned old = xb_add(&bar[XB_XSUB(b.x)], 1u);
;         const unsigned gen = old / nloc;
;         if (old + 1u == (gen + 1u) * nloc) {
;             __builtin_amdgcn_fence(__ATOMIC_RELEASE, "agent");
;             asm volatile("s_waitcnt vmcnt(0)" ::: "memory");
;             const unsigned og = xb_add(&bar[XB_TOP], 1u);
;             const unsigned tg = og / nx;
;             if (og + 1u == (tg + 1u) * nx) xb_add(&bar[XB_TOPGEN], 1u);
;             else XB_SPIN(xb_ld(&bar[XB_TOPGEN]) == tg, bar);
;             __builtin_amdgcn_fence(__ATOMIC_ACQUIRE, "agent");
;             xb_add(&bar[XB_XGEN(b.x)], 1u);
;             asm volatile("s_waitcnt vmcnt(0)" ::: "memory");
;         } else {
;             XB_SPIN(xb_ld(&bar[XB_XGEN(b.x)]) <= gen, bar);
;             __builtin_amdgcn_fence(__ATOMIC_ACQUIRE, "agent");
;             asm volatile("s_waitcnt vmcnt(0)" ::: "memory");
;         }
.LBB0_309:
	s_lshl_b32 s12, s33, 8
	s_add_u32 s12, s52, s12
	s_addc_u32 s13, s53, 0
	v_mov_b32_e32 v2, 0x1000
	v_mov_b32_e32 v4, 1
	global_atomic_add v4, v2, v4, s[12:13] offset:1024 sc0
	v_cvt_f32_u32_e32 v2, v3
	v_sub_u32_e32 v5, 0, v3
	v_rcp_iflag_f32_e32 v2, v2
	s_nop 0
	v_mul_f32_e32 v2, 0x4f7ffffe, v2
	v_cvt_u32_f32_e32 v2, v2
	v_mul_lo_u32 v5, v5, v2
	v_mul_hi_u32 v5, v2, v5
	v_add_u32_e32 v2, v2, v5
	s_waitcnt vmcnt(0)
	v_mul_hi_u32 v2, v4, v2
	v_mul_lo_u32 v5, v2, v3
	v_sub_u32_e32 v5, v4, v5
	v_add_u32_e32 v6, 1, v2
	v_cmp_ge_u32_e32 vcc, v5, v3
	v_add_u32_e32 v4, 1, v4
	s_nop 0
	v_cndmask_b32_e32 v2, v2, v6, vcc
	v_sub_u32_e32 v6, v5, v3
	v_cndmask_b32_e32 v5, v5, v6, vcc
	v_add_u32_e32 v6, 1, v2
	v_cmp_ge_u32_e32 vcc, v5, v3
	s_nop 1
	v_cndmask_b32_e32 v2, v2, v6, vcc
	v_mul_lo_u32 v5, v3, v2
	v_add_u32_e32 v3, v5, v3
	v_cmp_ne_u32_e32 vcc, v4, v3
	s_and_saveexec_b64 s[14:15], vcc
	s_xor_b64 s[14:15], exec, s[14:15]
	s_cbranch_execz .LBB0_323
	s_waitcnt lgkmcnt(0)
	v_mov_b32_e32 v1, 0x3100
	global_load_dword v1, v1, s[52:53] offset:1024 sc1
	s_add_u32 s22, s52, 0x3500
	s_addc_u32 s23, s53, 0
	s_waitcnt vmcnt(0)
	v_cmp_le_u32_e32 vcc, v1, v2
	s_and_saveexec_b64 s[18:19], vcc
	s_cbranch_execz .LBB0_322
	s_mov_b32 s36, 1
	s_mov_b64 s[24:25], 0
	v_mov_b32_e32 v1, 0
	s_branch .LBB0_313

; __device__ __forceinline__ unsigned xb_ld(unsigned* p)              { return __hip_atomic_load(p, __ATOMIC_RELAXED, __HIP_MEMORY_SCOPE_AGENT); }
; __device__ __forceinline__ unsigned xb_add(unsigned* p, unsigned v) { return __hip_atomic_fetch_add(p, v, __ATOMIC_RELAXED, __HIP_MEMORY_SCOPE_AGENT); }
; #define XB_SPIN(cond, bar) do { unsigned _sp = 0; while (cond) { __builtin_amdgcn_s_sleep(1); \
;     if ((++_sp & 255u) == 0u) { if (xb_ld(&(bar)[XB_TMO])) break; if (_sp > XB_SPIN_CAP) { atomicAdd(&(bar)[XB_TMO], 1u); break; } } } } while (0)
; __device__ __forceinline__ void xcd_barrier(const XcdBarrier& b) {
;     ...
;         const unsigned old = xb_add(&bar[XB_XSUB(b.x)], 1u);
;         const unsigned gen = old / nloc;
;         if (old + 1u == (gen + 1u) * nloc) {
;             __builtin_amdgcn_fence(__ATOMIC_RELEASE, "agent");
;             asm volatile("s_waitcnt vmcnt(0)" ::: "memory");
;             const unsigned og = xb_add(&bar[XB_TOP], 1u);
;             const unsigned tg = og / nx;
;             if (og + 1u == (tg + 1u) * nx) xb_add(&bar[XB_TOPGEN], 1u);
;             else XB_SPIN(xb_ld(&bar[XB_TOPGEN]) == tg, bar);
;             __builtin_amdgcn_fence(__ATOMIC_ACQUIRE, "agent");
;             xb_add(&bar[XB_XGEN(b.x)], 1u);
;             asm volatile("s_waitcnt vmcnt(0)" ::: "memory");
;         } else {
;             XB_SPIN(xb_ld(&bar[XB_XGEN(b.x)]) <= gen, bar);
;             __builtin_amdgcn_fence(__ATOMIC_ACQUIRE, "agent");
;             asm volatile("s_waitcnt vmcnt(0)" ::: "memory");
;         }
.LBB0_402:
	s_lshl_b32 s12, s33, 8
	s_add_u32 s12, s52, s12
	s_addc_u32 s13, s53, 0
	v_mov_b32_e32 v2, 0x1000
	v_mov_b32_e32 v4, 1
	global_atomic_add v4, v2, v4, s[12:13] offset:1024 sc0
	v_cvt_f32_u32_e32 v2, v3
	v_sub_u32_e32 v5, 0, v3
	v_rcp_iflag_f32_e32 v2, v2
	s_nop 0
	v_mul_f32_e32 v2, 0x4f7ffffe, v2
	v_cvt_u32_f32_e32 v2, v2
	v_mul_lo_u32 v5, v5, v2
	v_mul_hi_u32 v5, v2, v5
	v_add_u32_e32 v2, v2, v5
	s_waitcnt vmcnt(0)
	v_mul_hi_u32 v2, v4, v2
	v_mul_lo_u32 v5, v2, v3
	v_sub_u32_e32 v5, v4, v5
	v_add_u32_e32 v6, 1, v2
	v_cmp_ge_u32_e32 vcc, v5, v3
	v_add_u32_e32 v4, 1, v4
	s_nop 0
	v_cndmask_b32_e32 v2, v2, v6, vcc
	v_sub_u32_e32 v6, v5, v3
	v_cndmask_b32_e32 v5, v5, v6, vcc
	v_add_u32_e32 v6, 1, v2
	v_cmp_ge_u32_e32 vcc, v5, v3
	s_nop 1
	v_cndmask_b32_e32 v2, v2, v6, vcc
	v_mul_lo_u32 v5, v3, v2
	v_add_u32_e32 v3, v5, v3
	v_cmp_ne_u32_e32 vcc, v4, v3
	s_and_saveexec_b64 s[14:15], vcc
	s_xor_b64 s[14:15], exec, s[14:15]
	s_cbranch_execz .LBB0_416
	s_waitcnt lgkmcnt(0)
	v_mov_b32_e32 v1, 0x3100
	global_load_dword v1, v1, s[52:53] offset:1024 sc1
	s_add_u32 s18, s52, 0x3500
	s_addc_u32 s19, s53, 0
	s_waitcnt vmcnt(0)
	v_cmp_le_u32_e32 vcc, v1, v2
	s_and_saveexec_b64 s[16:17], vcc
	s_cbranch_execz .LBB0_415
	s_mov_b32 s30, 1
	s_mov_b64 s[20:21], 0
	v_mov_b32_e32 v1, 0
	s_branch .LBB0_406

; __device__ __forceinline__ unsigned xb_ld(unsigned* p)              { return __hip_atomic_load(p, __ATOMIC_RELAXED, __HIP_MEMORY_SCOPE_AGENT); }
; __device__ __forceinline__ unsigned xb_add(unsigned* p, unsigned v) { return __hip_atomic_fetch_add(p, v, __ATOMIC_RELAXED, __HIP_MEMORY_SCOPE_AGENT); }
; #define XB_SPIN(cond, bar) do { unsigned _sp = 0; while (cond) { __builtin_amdgcn_s_sleep(1); \
;     if ((++_sp & 255u) == 0u) { if (xb_ld(&(bar)[XB_TMO])) break; if (_sp > XB_SPIN_CAP) { atomicAdd(&(bar)[XB_TMO], 1u); break; } } } } while (0)
; __device__ __forceinline__ void xcd_barrier(const XcdBarrier& b) {
;     ...
;         const unsigned old = xb_add(&bar[XB_XSUB(b.x)], 1u);
;         const unsigned gen = old / nloc;
;         if (old + 1u == (gen + 1u) * nloc) {
;             __builtin_amdgcn_fence(__ATOMIC_RELEASE, "agent");
;             asm volatile("s_waitcnt vmcnt(0)" ::: "memory");
;             const unsigned og = xb_add(&bar[XB_TOP], 1u);
;             const unsigned tg = og / nx;
;             if (og + 1u == (tg + 1u) * nx) xb_add(&bar[XB_TOPGEN], 1u);
;             else XB_SPIN(xb_ld(&bar[XB_TOPGEN]) == tg, bar);
;             __builtin_amdgcn_fence(__ATOMIC_ACQUIRE, "agent");
;             xb_add(&bar[XB_XGEN(b.x)], 1u);
;             asm volatile("s_waitcnt vmcnt(0)" ::: "memory");
;         } else {
;             XB_SPIN(xb_ld(&bar[XB_XGEN(b.x)]) <= gen, bar);
;             __builtin_amdgcn_fence(__ATOMIC_ACQUIRE, "agent");
;             asm volatile("s_waitcnt vmcnt(0)" ::: "memory");
;         }
.LBB0_503:
	s_lshl_b32 s8, s33, 8
	s_add_u32 s8, s52, s8
	s_addc_u32 s9, s53, 0
	v_mov_b32_e32 v2, 0x1000
	v_mov_b32_e32 v4, 1
	global_atomic_add v4, v2, v4, s[8:9] offset:1024 sc0
	v_cvt_f32_u32_e32 v2, v3
	v_sub_u32_e32 v5, 0, v3
	v_rcp_iflag_f32_e32 v2, v2
	s_nop 0
	v_mul_f32_e32 v2, 0x4f7ffffe, v2
	v_cvt_u32_f32_e32 v2, v2
	v_mul_lo_u32 v5, v5, v2
	v_mul_hi_u32 v5, v2, v5
	v_add_u32_e32 v2, v2, v5
	s_waitcnt vmcnt(0)
	v_mul_hi_u32 v2, v4, v2
	v_mul_lo_u32 v5, v2, v3
	v_sub_u32_e32 v5, v4, v5
	v_add_u32_e32 v6, 1, v2
	v_cmp_ge_u32_e32 vcc, v5, v3
	v_add_u32_e32 v4, 1, v4
	s_nop 0
	v_cndmask_b32_e32 v2, v2, v6, vcc
	v_sub_u32_e32 v6, v5, v3
	v_cndmask_b32_e32 v5, v5, v6, vcc
	v_add_u32_e32 v6, 1, v2
	v_cmp_ge_u32_e32 vcc, v5, v3
	s_nop 1
	v_cndmask_b32_e32 v2, v2, v6, vcc
	v_mul_lo_u32 v5, v3, v2
	v_add_u32_e32 v3, v5, v3
	v_cmp_ne_u32_e32 vcc, v4, v3
	s_and_saveexec_b64 s[10:11], vcc
	s_xor_b64 s[10:11], exec, s[10:11]
	s_cbranch_execz .LBB0_517
	s_waitcnt lgkmcnt(0)
	v_mov_b32_e32 v1, 0x3100
	global_load_dword v1, v1, s[52:53] offset:1024 sc1
	s_add_u32 s14, s52, 0x3500
	s_addc_u32 s15, s53, 0
	s_waitcnt vmcnt(0)
	v_cmp_le_u32_e32 vcc, v1, v2
	s_and_saveexec_b64 s[12:13], vcc
	s_cbranch_execz .LBB0_516
	s_mov_b32 s26, 1
	s_mov_b64 s[16:17], 0
	v_mov_b32_e32 v1, 0
	s_branch .LBB0_507

; __device__ __forceinline__ unsigned xb_ld(unsigned* p)              { return __hip_atomic_load(p, __ATOMIC_RELAXED, __HIP_MEMORY_SCOPE_AGENT); }
; __device__ __forceinline__ unsigned xb_add(unsigned* p, unsigned v) { return __hip_atomic_fetch_add(p, v, __ATOMIC_RELAXED, __HIP_MEMORY_SCOPE_AGENT); }
; #define XB_SPIN(cond, bar) do { unsigned _sp = 0; while (cond) { __builtin_amdgcn_s_sleep(1); \
;     if ((++_sp & 255u) == 0u) { if (xb_ld(&(bar)[XB_TMO])) break; if (_sp > XB_SPIN_CAP) { atomicAdd(&(bar)[XB_TMO], 1u); break; } } } } while (0)
; __device__ __forceinline__ void xcd_barrier(const XcdBarrier& b) {
;     ...
;         const unsigned old = xb_add(&bar[XB_XSUB(b.x)], 1u);
;         const unsigned gen = old / nloc;
;         if (old + 1u == (gen + 1u) * nloc) {
;             __builtin_amdgcn_fence(__ATOMIC_RELEASE, "agent");
;             asm volatile("s_waitcnt vmcnt(0)" ::: "memory");
;             const unsigned og = xb_add(&bar[XB_TOP], 1u);
;             const unsigned tg = og / nx;
;             if (og + 1u == (tg + 1u) * nx) xb_add(&bar[XB_TOPGEN], 1u);
;             else XB_SPIN(xb_ld(&bar[XB_TOPGEN]) == tg, bar);
;             __builtin_amdgcn_fence(__ATOMIC_ACQUIRE, "agent");
;             xb_add(&bar[XB_XGEN(b.x)], 1u);
;             asm volatile("s_waitcnt vmcnt(0)" ::: "memory");
;         } else {
;             XB_SPIN(xb_ld(&bar[XB_XGEN(b.x)]) <= gen, bar);
;             __builtin_amdgcn_fence(__ATOMIC_ACQUIRE, "agent");
;             asm volatile("s_waitcnt vmcnt(0)" ::: "memory");
;         }
.LBB0_574:
	s_lshl_b32 s6, s33, 8
	s_add_u32 s6, s52, s6
	s_addc_u32 s7, s53, 0
	v_mov_b32_e32 v2, 0x1000
	v_mov_b32_e32 v4, 1
	global_atomic_add v4, v2, v4, s[6:7] offset:1024 sc0
	v_cvt_f32_u32_e32 v2, v3
	v_sub_u32_e32 v5, 0, v3
	v_rcp_iflag_f32_e32 v2, v2
	s_nop 0
	v_mul_f32_e32 v2, 0x4f7ffffe, v2
	v_cvt_u32_f32_e32 v2, v2
	v_mul_lo_u32 v5, v5, v2
	v_mul_hi_u32 v5, v2, v5
	v_add_u32_e32 v2, v2, v5
	s_waitcnt vmcnt(0)
	v_mul_hi_u32 v2, v4, v2
	v_mul_lo_u32 v5, v2, v3
	v_sub_u32_e32 v5, v4, v5
	v_add_u32_e32 v6, 1, v2
	v_cmp_ge_u32_e32 vcc, v5, v3
	v_add_u32_e32 v4, 1, v4
	s_nop 0
	v_cndmask_b32_e32 v2, v2, v6, vcc
	v_sub_u32_e32 v6, v5, v3
	v_cndmask_b32_e32 v5, v5, v6, vcc
	v_add_u32_e32 v6, 1, v2
	v_cmp_ge_u32_e32 vcc, v5, v3
	s_nop 1
	v_cndmask_b32_e32 v2, v2, v6, vcc
	v_mul_lo_u32 v5, v3, v2
	v_add_u32_e32 v3, v5, v3
	v_cmp_ne_u32_e32 vcc, v4, v3
	s_and_saveexec_b64 s[8:9], vcc
	s_xor_b64 s[8:9], exec, s[8:9]
	s_cbranch_execz .LBB0_588
	s_waitcnt lgkmcnt(0)
	v_mov_b32_e32 v1, 0x3100
	global_load_dword v1, v1, s[52:53] offset:1024 sc1
	s_add_u32 s12, s52, 0x3500
	s_addc_u32 s13, s53, 0
	s_waitcnt vmcnt(0)
	v_cmp_le_u32_e32 vcc, v1, v2
	s_and_saveexec_b64 s[10:11], vcc
	s_cbranch_execz .LBB0_587
	s_mov_b32 s24, 1
	s_mov_b64 s[14:15], 0
	v_mov_b32_e32 v1, 0
	s_branch .LBB0_578
